# attention softmax: cross-row max / sum exchanges (xor 16, xor 32) done with v_permlane16_swap / v_permlane32_swap instead of ds_bpermute round trips (3 LDS latencies fewer per step)
# speedup vs baseline: 1.0091x; 1.0091x over previous
; __device__ __forceinline__ float fast_exp2(float x) { return __builtin_amdgcn_exp2f(x); }
; __device__ __forceinline__ u32x4 pack8(f32x4 a, f32x4 b) { u32x4 w; w.x = cvt_pk_bf16(a[0], a[1]); w.y = cvt_pk_bf16(a[2], a[3]); w.z = cvt_pk_bf16(b[0], b[1]); w.w = cvt_pk_bf16(b[2], b[3]); return w; }
; #define SCHED_FENCE() __builtin_amdgcn_sched_barrier(0)
; #define ATT_K_PIECE(h_, row_, kg_) do { const int key = (kg_) * 8 + lr; \
;         __builtin_amdgcn_global_load_lds((const __attribute__((address_space(1))) unsigned*)(Kb + ((size_t)(row_) * 64 + key) * 1024 + (h_) * 64 + 8 * (lc ^ att_fk(key))), (LAS unsigned*)(KL + ((row_) & 7) * 8192 + (kg_) * 1024), 16, 0, 0); } while (0)
; #define ATT_BAR() do { asm volatile("s_waitcnt lgkmcnt(0)" ::: "memory"); __builtin_amdgcn_s_barrier(); asm volatile("" ::: "memory"); } while (0)
; __device__ __forceinline__ void attn_phase(const bf16_t* Q, const bf16_t* Kb, const bf16_t* VTa, const float* rpb, bf16_t* Y, LAS unsigned char* lds, int bx, int G, int tid, int wave, int lane) {
;     ...
;                     for (int idx = 0; idx < 4; ++idx) { a[idx] += bia[4 * ta + idx]; mx = fmaxf(mx, a[idx]); }
;                     s[ii][ta] = a;
;                 }
;             }
;             ATT_BAR();
;             SCHED_FENCE();
;             if (newrow) ATT_K_PIECE(h, rs + 8, wave);
;             SCHED_FENCE();
;             if (has_next) { const bf16_t* qp = Q + (size_t)((r + 1) * 64 + c) * 1024 + h * 64 + 8 * fq; qf0 = *(const bf16x8*)qp; qf1 = *(const bf16x8*)(qp + 32); }
;             SCHED_FENCE();
;             mx = fmaxf(mx, __shfl_xor(mx, 16)); mx = fmaxf(mx, __shfl_xor(mx, 32));
;             float l = 0.f;
;             bf16x8 pb[4];
; #pragma unroll
;             for (int ii = 0; ii < 4; ++ii) {
;                 f32x4 p0, p1;
; #pragma unroll
;                 for (int idx = 0; idx < 4; ++idx) { p0[idx] = fast_exp2((s[ii][0][idx] - mx) * 1.4426950409f); p1[idx] = fast_exp2((s[ii][1][idx] - mx) * 1.4426950409f); }
;                 l += (p0[0] + p0[1]) + (p0[2] + p0[3]) + (p1[0] + p1[1]) + (p1[2] + p1[3]);
;                 const u32x4 pw = pack8(p0, p1); pb[ii] = __builtin_bit_cast(bf16x8, pw);
;             }
;             l += __shfl_xor(l, 16); l += __shfl_xor(l, 32);
.LBB0_453:
	v_pk_add_f32 v[10:11], v[10:11], v[202:203]
	v_pk_add_f32 v[12:13], v[12:13], v[204:205]
	v_pk_add_f32 v[14:15], v[14:15], v[206:207]
	v_pk_add_f32 v[16:17], v[16:17], v[208:209]
	v_pk_add_f32 v[18:19], v[18:19], v[210:211]
	v_pk_add_f32 v[20:21], v[20:21], v[212:213]
	v_pk_add_f32 v[22:23], v[22:23], v[214:215]
	v_pk_add_f32 v[24:25], v[24:25], v[216:217]
	v_pk_add_f32 v[26:27], v[26:27], v[102:103]
	v_pk_add_f32 v[28:29], v[28:29], v[104:105]
	v_pk_add_f32 v[30:31], v[30:31], v[106:107]
	v_pk_add_f32 v[32:33], v[32:33], v[108:109]
	v_pk_add_f32 v[34:35], v[34:35], v[110:111]
	v_pk_add_f32 v[36:37], v[36:37], v[112:113]
	v_pk_add_f32 v[224:225], v[2:3], v[114:115]
	v_pk_add_f32 v[226:227], v[4:5], v[116:117]
	v_max3_f32 v221, v10, s6, v11
	v_max3_f32 v221, v221, v12, v13
	v_max3_f32 v221, v221, v14, v15
	v_max3_f32 v221, v221, v16, v17
	v_max3_f32 v221, v221, v18, v19
	v_max3_f32 v221, v221, v20, v21
	v_max3_f32 v221, v221, v22, v23
	v_max3_f32 v221, v221, v24, v25
	v_max3_f32 v221, v221, v26, v27
	v_max3_f32 v221, v221, v28, v29
	v_max3_f32 v221, v221, v30, v31
	v_max3_f32 v221, v221, v32, v33
	v_max3_f32 v221, v221, v34, v35
	v_max3_f32 v221, v221, v36, v37
	v_max3_f32 v221, v221, v224, v225
	v_max3_f32 v221, v221, v226, v227
	v_add_u32_e32 v230, 64, v98
	v_ashrrev_i32_e32 v231, 31, v230
	v_lshlrev_b64 v[228:229], 11, v[230:231]
	v_lshl_add_u64 v[228:229], v[92:93], 0, v[228:229]
	global_load_dwordx4 v[6:9], v[228:229], off
	s_nop 0
	global_load_dwordx4 v[2:5], v[228:229], off offset:64
	v_and_b32_e32 v239, 64, v241
	v_xor_b32_e32 v238, 16, v241
	v_add_u32_e32 v239, 64, v239
	v_cmp_lt_i32_e32 vcc, v238, v239
	v_xor_b32_e32 v246, 32, v241
	s_nop 0
	v_cndmask_b32_e32 v238, v241, v238, vcc
	v_lshlrev_b32_e32 v238, 2, v238
	v_cmp_lt_i32_e32 vcc, v246, v239
	v_mov_b32_e32 v247, v221
	v_mov_b32_e32 v250, v221
	v_mov_b32_e32 v248, 0x3fb8aa3b
	v_cndmask_b32_e32 v239, v241, v246, vcc
	v_permlane16_swap_b32 v247, v250
	v_lshlrev_b32_e32 v239, 2, v239
	v_max_f32_e32 v221, v247, v250
	v_mov_b32_e32 v247, v221
	v_mov_b32_e32 v250, v221
	s_nop 1
	v_permlane32_swap_b32 v247, v250
	v_max_f32_e32 v221, v247, v250
	v_mul_f32_e32 v222, 0xbfb8aa3b, v221
	v_pk_fma_f32 v[10:11], v[10:11], v[248:249], v[222:223] op_sel_hi:[1,0,0]
	v_pk_fma_f32 v[12:13], v[12:13], v[248:249], v[222:223] op_sel_hi:[1,0,0]
	v_pk_fma_f32 v[14:15], v[14:15], v[248:249], v[222:223] op_sel_hi:[1,0,0]
	v_pk_fma_f32 v[16:17], v[16:17], v[248:249], v[222:223] op_sel_hi:[1,0,0]
	v_pk_fma_f32 v[18:19], v[18:19], v[248:249], v[222:223] op_sel_hi:[1,0,0]
	v_pk_fma_f32 v[20:21], v[20:21], v[248:249], v[222:223] op_sel_hi:[1,0,0]
	v_pk_fma_f32 v[22:23], v[22:23], v[248:249], v[222:223] op_sel_hi:[1,0,0]
	v_pk_fma_f32 v[24:25], v[24:25], v[248:249], v[222:223] op_sel_hi:[1,0,0]
	v_pk_fma_f32 v[26:27], v[26:27], v[248:249], v[222:223] op_sel_hi:[1,0,0]
	v_pk_fma_f32 v[28:29], v[28:29], v[248:249], v[222:223] op_sel_hi:[1,0,0]
	v_pk_fma_f32 v[30:31], v[30:31], v[248:249], v[222:223] op_sel_hi:[1,0,0]
	v_pk_fma_f32 v[32:33], v[32:33], v[248:249], v[222:223] op_sel_hi:[1,0,0]
	v_pk_fma_f32 v[34:35], v[34:35], v[248:249], v[222:223] op_sel_hi:[1,0,0]
	v_pk_fma_f32 v[36:37], v[36:37], v[248:249], v[222:223] op_sel_hi:[1,0,0]
	v_pk_fma_f32 v[224:225], v[224:225], v[248:249], v[222:223] op_sel_hi:[1,0,0]
	v_pk_fma_f32 v[226:227], v[226:227], v[248:249], v[222:223] op_sel_hi:[1,0,0]
	v_exp_f32_e32 v10, v10
	v_exp_f32_e32 v11, v11
	v_exp_f32_e32 v12, v12
	v_exp_f32_e32 v13, v13
	v_exp_f32_e32 v14, v14
	v_exp_f32_e32 v15, v15
	v_exp_f32_e32 v16, v16
	v_exp_f32_e32 v17, v17
	v_exp_f32_e32 v18, v18
	v_exp_f32_e32 v19, v19
	v_exp_f32_e32 v20, v20
	v_exp_f32_e32 v21, v21
	v_exp_f32_e32 v22, v22
	v_exp_f32_e32 v23, v23
	v_exp_f32_e32 v24, v24
	v_exp_f32_e32 v25, v25
	v_exp_f32_e32 v26, v26
	v_exp_f32_e32 v27, v27
	v_exp_f32_e32 v28, v28
	v_exp_f32_e32 v29, v29
	v_exp_f32_e32 v30, v30
	v_exp_f32_e32 v31, v31
	v_exp_f32_e32 v32, v32
	v_exp_f32_e32 v33, v33
	v_exp_f32_e32 v34, v34
	v_exp_f32_e32 v35, v35
	v_exp_f32_e32 v36, v36
	v_exp_f32_e32 v37, v37
	v_exp_f32_e32 v224, v224
	v_exp_f32_e32 v225, v225
	v_exp_f32_e32 v226, v226
	v_exp_f32_e32 v227, v227
	v_pk_add_f32 v[250:251], v[10:11], v[12:13]
	v_pk_add_f32 v[252:253], v[14:15], v[16:17]
	v_pk_add_f32 v[246:247], v[18:19], v[20:21]
	v_pk_add_f32 v[250:251], v[250:251], v[246:247]
	v_pk_add_f32 v[246:247], v[22:23], v[24:25]
	v_pk_add_f32 v[252:253], v[252:253], v[246:247]
	v_pk_add_f32 v[246:247], v[26:27], v[28:29]
	v_pk_add_f32 v[250:251], v[250:251], v[246:247]
	v_pk_add_f32 v[246:247], v[30:31], v[32:33]
	v_pk_add_f32 v[252:253], v[252:253], v[246:247]
	v_pk_add_f32 v[246:247], v[34:35], v[36:37]
	v_pk_add_f32 v[250:251], v[250:251], v[246:247]
	v_pk_add_f32 v[246:247], v[224:225], v[226:227]
	v_pk_add_f32 v[252:253], v[252:253], v[246:247]
	v_pk_add_f32 v[250:251], v[250:251], v[252:253]
	v_cvt_pk_bf16_f32 v10, v10, v11
	v_cvt_pk_bf16_f32 v11, v12, v13
	v_cvt_pk_bf16_f32 v12, v14, v15
	v_cvt_pk_bf16_f32 v13, v16, v17
	v_cvt_pk_bf16_f32 v14, v18, v19
	v_cvt_pk_bf16_f32 v15, v20, v21
	v_cvt_pk_bf16_f32 v16, v22, v23
	v_cvt_pk_bf16_f32 v17, v24, v25
	v_cvt_pk_bf16_f32 v18, v26, v27
	v_cvt_pk_bf16_f32 v19, v28, v29
	v_cvt_pk_bf16_f32 v20, v30, v31
	v_cvt_pk_bf16_f32 v21, v32, v33
	v_cvt_pk_bf16_f32 v26, v34, v35
	v_cvt_pk_bf16_f32 v27, v36, v37
	v_cvt_pk_bf16_f32 v28, v224, v225
	v_cvt_pk_bf16_f32 v29, v226, v227
	v_add_f32_e32 v22, v250, v251
	v_mov_b32_e32 v32, v221
	v_mov_b32_e32 v247, v22
	v_mov_b32_e32 v250, v22
	v_mov_b32_e32 v30, v230
	v_mov_b32_e32 v31, v238
	v_permlane16_swap_b32 v247, v250
	v_mov_b32_e32 v34, v239
	v_add_f32_e32 v22, v247, v250
	ds_bpermute_b32 v23, v239, v22
	v_cndmask_b32_e64 v24, 0, 1, s[56:57]
	v_cmp_ne_u32_e64 s[60:61], 1, v24
	s_andn2_b64 vcc, exec, s[56:57]
	s_mov_b64 s[56:57], -1
	s_cbranch_vccnz .LBB0_455
	s_waitcnt vmcnt(3)
	s_mov_b64 s[56:57], 0
